# diff fast loop: fourth P chunk kept in place in the freed l registers v92-95 (no per-tile 4-mov copy), its row-sum MFMA pair last followed by its four cvts
# baseline (speedup 1.0000x reference)
.Lf_459:
	v_mfma_f32_32x32x16_bf16 v[64:79], v[176:179], v[140:143], v[64:79]
	ds_read_b64_tr_b16 v[128:129], v0 offset:24576
	ds_read_b64_tr_b16 v[130:131], v0 offset:25088
	v_exp_f32_e32 v14, v112
	v_mfma_f32_32x32x16_bf16 v[64:79], v[172:175], v[136:139], v[64:79]
	ds_read_b64_tr_b16 v[172:173], v0 offset:25600
	ds_read_b64_tr_b16 v[174:175], v0 offset:26112
	v_exp_f32_e32 v15, v96
	v_mfma_f32_32x32x16_bf16 v[64:79], v[168:171], v[132:135], v[64:79]
	ds_read_b64_tr_b16 v[168:169], v0 offset:26624
	ds_read_b64_tr_b16 v[170:171], v0 offset:27136
	v_exp_f32_e32 v96, v113
	v_mfma_f32_32x32x16_bf16 v[64:79], v[164:167], v[92:95], v[64:79]
	ds_read_b64_tr_b16 v[164:165], v0 offset:27648
	ds_read_b64_tr_b16 v[166:167], v0 offset:28160
	v_exp_f32_e32 v97, v97
	v_mfma_f32_32x32x16_bf16 v[48:63], v[160:163], v[140:143], v[48:63]
	ds_read_b64_tr_b16 v[160:161], v0 offset:28672
	ds_read_b64_tr_b16 v[162:163], v0 offset:29184
	v_exp_f32_e32 v112, v114
	v_mfma_f32_32x32x16_bf16 v[48:63], v[10:13], v[136:139], v[48:63]
	ds_read_b64_tr_b16 v[10:11], v0 offset:29696
	ds_read_b64_tr_b16 v[12:13], v0 offset:30208
	v_exp_f32_e32 v98, v98
	v_mfma_f32_32x32x16_bf16 v[48:63], v[6:9], v[132:135], v[48:63]
	ds_read_b64_tr_b16 v[6:7], v0 offset:30720
	ds_read_b64_tr_b16 v[8:9], v0 offset:31232
	v_exp_f32_e32 v113, v115
	v_mfma_f32_32x32x16_bf16 v[48:63], v[2:5], v[92:95], v[48:63]
	ds_read_b64_tr_b16 v[2:3], v0 offset:31744
	ds_read_b64_tr_b16 v[4:5], v0 offset:32256
	v_exp_f32_e32 v0, v99
	s_waitcnt lgkmcnt(14)
	v_mfma_f32_32x32x16_bf16 v[32:47], v[128:131], v[140:143], v[32:47]
	v_exp_f32_e32 v99, v116
	v_exp_f32_e32 v100, v100
	v_exp_f32_e32 v114, v117
	s_waitcnt lgkmcnt(12)
	v_mfma_f32_32x32x16_bf16 v[32:47], v[172:175], v[136:139], v[32:47]
	v_exp_f32_e32 v101, v101
	v_exp_f32_e32 v115, v118
	v_exp_f32_e32 v102, v102
	s_waitcnt lgkmcnt(10)
	v_mfma_f32_32x32x16_bf16 v[32:47], v[168:171], v[132:135], v[32:47]
	v_exp_f32_e32 v116, v119
	v_exp_f32_e32 v103, v103
	v_exp_f32_e32 v117, v120
	s_waitcnt lgkmcnt(8)
	v_mfma_f32_32x32x16_bf16 v[32:47], v[164:167], v[92:95], v[32:47]
	v_exp_f32_e32 v104, v104
	v_exp_f32_e32 v118, v121
	v_exp_f32_e32 v105, v105
	s_waitcnt lgkmcnt(6)
	v_mfma_f32_32x32x16_bf16 v[16:31], v[160:163], v[140:143], v[16:31]
	v_exp_f32_e32 v119, v122
	v_exp_f32_e32 v106, v106
	v_exp_f32_e32 v120, v123
	s_waitcnt lgkmcnt(4)
	v_mfma_f32_32x32x16_bf16 v[16:31], v[10:13], v[136:139], v[16:31]
	v_exp_f32_e32 v10, v107
	v_exp_f32_e32 v11, v124
	v_exp_f32_e32 v12, v108
	s_waitcnt lgkmcnt(2)
	v_mfma_f32_32x32x16_bf16 v[16:31], v[6:9], v[132:135], v[16:31]
	v_exp_f32_e32 v6, v125
	v_exp_f32_e32 v7, v109
	v_exp_f32_e32 v8, v126
	s_waitcnt lgkmcnt(0)
	v_mfma_f32_32x32x16_bf16 v[16:31], v[2:5], v[92:95], v[16:31]
	v_exp_f32_e32 v107, v110
	s_nop 0
	v_mfma_f32_4x4x4_16b_bf16 v[84:87], v[218:219], v[140:141], v[84:87]
	v_mfma_f32_4x4x4_16b_bf16 v[88:91], v[218:219], v[142:143], v[88:91]
	v_exp_f32_e32 v108, v127
	v_exp_f32_e32 v109, v111
	v_cvt_pk_bf16_f32 v140, v14, v96
	v_cvt_pk_bf16_f32 v143, v115, v116
	v_mfma_f32_4x4x4_16b_bf16 v[84:87], v[218:219], v[136:137], v[84:87]
	v_mfma_f32_4x4x4_16b_bf16 v[88:91], v[218:219], v[138:139], v[88:91]
	v_cvt_pk_bf16_f32 v141, v112, v113
	v_cvt_pk_bf16_f32 v136, v117, v118
	v_cvt_pk_bf16_f32 v137, v119, v120
	v_mfma_f32_4x4x4_16b_bf16 v[84:87], v[218:219], v[132:133], v[84:87]
	v_mfma_f32_4x4x4_16b_bf16 v[88:91], v[218:219], v[134:135], v[88:91]
	v_cvt_pk_bf16_f32 v132, v15, v97
	v_cvt_pk_bf16_f32 v138, v11, v6
	v_cvt_pk_bf16_f32 v133, v98, v0
	v_cvt_pk_bf16_f32 v142, v99, v114
	v_cvt_pk_bf16_f32 v134, v100, v101
	v_cvt_pk_bf16_f32 v135, v102, v103
	v_cvt_pk_bf16_f32 v139, v8, v108
	v_mfma_f32_4x4x4_16b_bf16 v[84:87], v[218:219], v[92:93], v[84:87]
	v_mfma_f32_4x4x4_16b_bf16 v[88:91], v[218:219], v[94:95], v[88:91]
	v_cvt_pk_bf16_f32 v92, v104, v105
	v_cvt_pk_bf16_f32 v93, v106, v10
	v_cvt_pk_bf16_f32 v94, v12, v7
	v_cvt_pk_bf16_f32 v95, v107, v109
	s_nop 0
	s_add_i32 s28, s28, 1
	s_add_i32 s13, s13, 1
	s_add_i32 s19, s19, 0x8000
	s_cmpk_eq_i32 s13, 0x45
	s_cbranch_scc1 .Lf_fold464

.Lf_foldrare:
	s_nop 4
	v_mov_b32_e32 v128, v92
	v_mov_b32_e32 v129, v93
	v_mov_b32_e32 v130, v94
	v_mov_b32_e32 v131, v95
	v_add_f32_e32 v84, v84, v88
	s_nop 0
	v_mov_b32_e32 v88, v84
	s_nop 1
	v_permlane32_swap_b32_e32 v88, v84
	s_nop 1
	v_add_f32_e32 v80, v84, v88
	s_nop 0
	v_mov_b32_e32 v81, v80
	v_mov_b32_e32 v82, v80
	v_mov_b32_e32 v83, v80
	v_mov_b32_e32 v84, v80
	v_mov_b32_e32 v85, v80
	v_mov_b32_e32 v86, v80
	v_mov_b32_e32 v87, v80
	v_mov_b32_e32 v88, v80
	v_mov_b32_e32 v89, v80
	v_mov_b32_e32 v90, v80
	v_mov_b32_e32 v91, v80
	v_mov_b32_e32 v92, v80
	v_mov_b32_e32 v93, v80
	v_mov_b32_e32 v94, v80
	v_mov_b32_e32 v95, v80
	s_nop 1
	s_branch .Lf_to463
.Lf_fold464:
	s_nop 4
	v_mov_b32_e32 v128, v92
	v_mov_b32_e32 v129, v93
	v_mov_b32_e32 v130, v94
	v_mov_b32_e32 v131, v95
	v_add_f32_e32 v84, v84, v88
	s_nop 0
	v_mov_b32_e32 v88, v84
	s_nop 1
	v_permlane32_swap_b32_e32 v88, v84
	s_nop 1
	v_add_f32_e32 v80, v84, v88
	s_nop 0
	v_mov_b32_e32 v81, v80
	v_mov_b32_e32 v82, v80
	v_mov_b32_e32 v83, v80
	v_mov_b32_e32 v84, v80
	v_mov_b32_e32 v85, v80
	v_mov_b32_e32 v86, v80
	v_mov_b32_e32 v87, v80
	v_mov_b32_e32 v88, v80
	v_mov_b32_e32 v89, v80
	v_mov_b32_e32 v90, v80
	v_mov_b32_e32 v91, v80
	v_mov_b32_e32 v92, v80
	v_mov_b32_e32 v93, v80
	v_mov_b32_e32 v94, v80
	v_mov_b32_e32 v95, v80
	s_nop 1
	s_branch .LBB0_464
	.p2align 6
